# prompt attention: every workgroup processes its long q block (15 - sb) first, so the 8 workgroups of a head stream the same K/V tiles in step (L2 reuse), then the short one
# baseline (speedup 1.0000x reference)
; __global__ void __launch_bounds__(NWAVES * 64, 2) mk_fwd(Args args) {
;     ...
;             for (int i = 0; i < 8; ++i) { const int qb = (i >> 2) ? 15 - s : s, j = (i >> 1) & 1, vh = i & 1;
;                 const bf16* Qp = Qb + (size_t)(b * 4096 + qb * 256) * 512 + (hd * 2 + j) * 64; const bf16* Kp = Kb + (size_t)(b * 4096) * 512 + (hd * 2 + j) * 64; const bf16* Vp = Vb + (size_t)(b * 4096) * 512 + (hd * 2 + vh) * 64;
;                 bf16* Op = ATTO + (size_t)(b * 4096 + qb * 256) * 1024 + ((hd * 2 + j) * 2 + vh) * 64;
;                 bf16* Mp = ((i & 3) == 3) ? H + (size_t)(b * 4096 + qb * 256) * 1024 + 512 + hd * 128 : nullptr;
;                 const bool more = i < 7; const int jn = ((i + 1) >> 1) & 1, vn = (i + 1) & 1;
;                 const bf16* nK = Kb + (size_t)(b * 4096) * 512 + (hd * 2 + jn) * 64; const bf16* nV = Vb + (size_t)(b * 4096) * 512 + (hd * 2 + vn) * 64;
;                 ring0 = attn_body::attn_unit<8, false>((const attn_body::bf16*)Qp, (const attn_body::bf16*)Kp, (const attn_body::bf16*)Vp, (attn_body::bf16*)Op, 4 * (qb + 1), -1, (char*)lds, ring0, primed,
.Lat_blk:
	s_sub_i32 s34, 15, s11
	s_cmp_eq_u32 s12, 0
	s_cselect_b32 s13, s34, s11
	s_lshl_b32 s15, s13, 2
	s_add_i32 s15, s15, 4
	s_lshr_b32 s34, s45, 1
	s_add_i32 s16, s15, s34
	s_sub_i32 s16, s16, 3
	s_mov_b32 s14, 0
